# speedup vs baseline: 1.0068x; 1.0068x over previous
; #define LAS __attribute__((address_space(3)))
; #define GAS __attribute__((address_space(1)))
; __device__ __forceinline__ void attn_unit(LAS unsigned char* lds, bf16_t* Qm, const bf16_t* __restrict__ Kb, const bf16_t* __restrict__ Vt,
;                                           int b, int h, int qb, int lgS, float lam, float oscale, const float* __restrict__ subg, float* stash) {
;     ...
;     for (int c = 0; c < 2; ++c) {
;         const bf16_t* qp = Qm + (size_t)(tok0 + r32) * MIXW + (2 * h + c) * 64 + hi * 8;
;         bf16x8 qf[4];
; #pragma unroll
;         for (int d0 = 0; d0 < 4; ++d0) qf[d0] = *(const GAS bf16x8*)(qp + d0 * 16);
; #pragma unroll
;         for (int i = 0; i < 4; ++i)
; #pragma unroll
;             for (int r = 0; r < 16; ++r) o[i][r] = 0.f;
;         float mhat, lrun;
;         f32x16 negm;
; #pragma unroll
;         for (int r = 0; r < 16; ++r) negm[r] = 0.f;
;         const bf16_t* kg = Kb + (size_t)((b << lgS) + (tid >> 3)) * 512 + (2 * h + c) * 64 + (tid & 7) * 8;
;         const bf16_t* vg0 = Vt + ((size_t)(b * 512 + h * 128 + (tid >> 3)) << lgS) + (tid & 7) * 8;
;         const bf16_t* vg1 = vg0 + ((size_t)64 << lgS);
;         u32x4 kreg, vreg0, vreg1;
;         {
;             kreg = *(const GAS u32x4*)kg; vreg0 = *(const GAS u32x4*)vg0; vreg1 = *(const GAS u32x4*)vg1;
;             const u32x4 k1 = *(const GAS u32x4*)(kg + (size_t)64 * 512), k2 = *(const GAS u32x4*)(kg + (size_t)2 * 64 * 512), v10 = *(const GAS u32x4*)(vg0 + 64), v11 = *(const GAS u32x4*)(vg1 + 64);
;             *(LAS u32x4*)(lds + kw) = kreg; *(LAS u32x4*)(lds + vw0) = vreg0; *(LAS u32x4*)(lds + vw1) = vreg1;
;             *(LAS u32x4*)(lds + KBUF + kw) = k1; *(LAS u32x4*)(lds + VBUF + vw0) = v10; *(LAS u32x4*)(lds + VBUF + vw1) = v11;
;             *(LAS u32x4*)(lds + 2 * KBUF + kw) = k2;
;             kreg = *(const GAS u32x4*)(kg + (size_t)3 * 64 * 512); vreg0 = *(const GAS u32x4*)(vg0 + 2 * 64); vreg1 = *(const GAS u32x4*)(vg1 + 2 * 64);
;         }
;         __syncthreads();
;         u32x4 pk[4]; bf16x8 kf[8]; bf16x8 vfa[4], vfb[4];
;         {
;             f32x16 p0, p1;
;             ATT_KRD(0, 0, 4);
;             ATT_QK(p0, p1);
.LBB0_334:
	s_cmp_eq_u32 s98, 0
	s_cbranch_scc1 .Lmy_noprio
	s_setprio 1
.Lmy_noprio:
	s_or_b32 s90, s25, s5
	s_lshl_b64 s[28:29], s[90:91], 1
	v_lshl_add_u64 v[12:13], v[228:229], 0, s[28:29]
	v_add_co_u32_e32 v4, vcc, 0x10000, v12
	v_lshl_add_u64 v[14:15], v[226:227], 0, s[28:29]
	s_nop 0
	v_addc_co_u32_e32 v5, vcc, 0, v13, vcc
	global_load_dwordx4 v[0:3], v[12:13], off
	s_nop 0
	global_load_dwordx4 v[4:7], v[4:5], off
	v_add_co_u32_e32 v8, vcc, 0x20000, v12
	v_add_u32_e32 v16, 0, v234
	s_nop 0
	v_addc_co_u32_e32 v9, vcc, 0, v13, vcc
	global_load_dwordx4 v[8:11], v[8:9], off
	s_nop 0
	global_load_dwordx4 v[136:139], v[14:15], off
	global_load_dwordx4 v[140:143], v[14:15], off offset:32
	global_load_dwordx4 v[144:147], v[14:15], off offset:64
	global_load_dwordx4 v[148:151], v[14:15], off offset:96
	v_add_co_u32_e32 v12, vcc, 0x30000, v12
	s_waitcnt vmcnt(8)
	v_mov_b64_e32 v[170:171], v[130:131]
	v_addc_co_u32_e32 v13, vcc, 0, v13, vcc
	global_load_dwordx4 v[152:155], v[12:13], off
	s_waitcnt vmcnt(8)
	v_mov_b64_e32 v[178:179], v[134:135]
	v_lshl_add_u64 v[238:239], v[236:237], 0, s[28:29]
	s_mov_b32 s56, 0x9000
	s_movk_i32 s50, 0x2100
	s_movk_i32 s29, 0x4200
	s_movk_i32 s25, 0x4800
	s_movk_i32 s90, 0xc0
	v_mov_b64_e32 v[168:169], v[128:129]
	v_mov_b64_e32 v[176:177], v[132:133]
	s_mov_b32 s28, 0
	s_mov_b32 s57, 0
	s_mov_b32 s60, 0
	s_waitcnt vmcnt(7)
	ds_write_b128 v248, v[0:3]
	ds_write_b128 v16, v[112:115] offset:25344
	ds_write_b128 v16, v[116:119] offset:34560
	s_waitcnt vmcnt(6)
	ds_write_b128 v248, v[4:7] offset:8448
	ds_write_b128 v16, v[120:123] offset:43776
	ds_write_b128 v16, v[124:127] offset:52992
	s_waitcnt vmcnt(5)
	ds_write_b128 v248, v[8:11] offset:16896
	s_waitcnt lgkmcnt(0)
	s_barrier
	ds_read_b128 v[0:3], v235
	ds_read_b128 v[18:21], v235 offset:512
	s_waitcnt vmcnt(4) lgkmcnt(1)
	v_mfma_f32_32x32x16_bf16 v[2:17], v[0:3], v[136:139], 0
	ds_read_b128 v[34:37], v235 offset:2112
	ds_read_b128 v[38:41], v235 offset:2624
	v_mov_b32_e32 v0, 0
	v_mov_b32_e32 v51, v0
	v_mov_b32_e32 v52, v0
	v_mov_b32_e32 v53, v0
	v_mov_b32_e32 v54, v0
	v_mov_b32_e32 v55, v0
	s_waitcnt lgkmcnt(2)
	v_mfma_f32_32x32x16_bf16 v[18:33], v[18:21], v[136:139], 0
	v_mov_b32_e32 v56, v0
	v_mov_b32_e32 v57, v0
	v_mov_b32_e32 v58, v0
	v_mov_b32_e32 v59, v0
	v_mov_b32_e32 v60, v0
	v_mov_b32_e32 v61, v0
	v_mov_b32_e32 v62, v0
	s_waitcnt vmcnt(3) lgkmcnt(1)
	v_mfma_f32_32x32x16_bf16 v[2:17], v[34:37], v[140:143], v[2:17]
	v_mov_b32_e32 v63, v0
	s_waitcnt lgkmcnt(0)
	v_mfma_f32_32x32x16_bf16 v[18:33], v[38:41], v[140:143], v[18:33]
	ds_read_b128 v[34:37], v235 offset:4224
	ds_read_b128 v[38:41], v235 offset:4736
	s_waitcnt vmcnt(2) lgkmcnt(1)
	v_mfma_f32_32x32x16_bf16 v[2:17], v[34:37], v[144:147], v[2:17]
	ds_read_b128 v[34:37], v235 offset:6336
	s_waitcnt lgkmcnt(1)
	v_mfma_f32_32x32x16_bf16 v[18:33], v[38:41], v[144:147], v[18:33]
	ds_read_b128 v[38:41], v235 offset:6848
	ds_read_b128 v[156:159], v235 offset:8448
	ds_read_b128 v[160:163], v235 offset:8960
	ds_read_b128 v[204:207], v235 offset:10560
	ds_read_b128 v[208:211], v235 offset:11072
	ds_read_b128 v[212:215], v235 offset:12672
	ds_read_b128 v[216:219], v235 offset:13184
	ds_read_b128 v[222:225], v235 offset:14784
	ds_read_b128 v[240:243], v235 offset:15296
	ds_read_b128 v[196:199], v220 offset:25344
	ds_read_b128 v[192:195], v220 offset:29952
	ds_read_b128 v[188:191], v220 offset:34560
	ds_read_b128 v[184:187], v220 offset:39168
	s_waitcnt lgkmcnt(0)
	s_barrier
; #define LAS __attribute__((address_space(3)))
; #define GAS __attribute__((address_space(1)))
; __device__ __forceinline__ void attn_unit(LAS unsigned char* lds, bf16_t* Qm, const bf16_t* __restrict__ Kb, const bf16_t* __restrict__ Vt,
;                                           int b, int h, int qb, int lgS, float lam, float oscale, const float* __restrict__ subg, float* stash) {
;     ...
;             float mx;
;             {
;                 float a_ = ATT_MX3(p0[0], p0[1], p1[0]), b_ = ATT_MX3(p0[2], p0[3], p1[1]); a_ = ATT_MX3(a_, p1[2], p1[3]);
; #pragma unroll
;                 for (int r = 4; r < 16; r += 4) { a_ = ATT_MX3(a_, p0[r], p0[r + 1]); b_ = ATT_MX3(b_, p0[r + 2], p0[r + 3]); a_ = ATT_MX3(a_, p1[r], p1[r + 1]); b_ = ATT_MX3(b_, p1[r + 2], p1[r + 3]); }
;                 const float m_ = __builtin_fmaxf(a_, b_);
;                 auto rr_ = __builtin_amdgcn_permlane32_swap(__float_as_uint(m_), __float_as_uint(m_), false, false);
;                 mx = __builtin_fmaxf(__uint_as_float(rr_[0]), __uint_as_float(rr_[1]));
;             }
;             mhat = mx;
; #pragma unroll
;             for (int r = 0; r < 16; ++r) negm[r] = -mx;
;             float sum = 0.f;
; #pragma unroll
;             for (int r = 0; r < 16; ++r) { p0[r] = __builtin_amdgcn_exp2f(p0[r] - mx); p1[r] = __builtin_amdgcn_exp2f(p1[r] - mx); sum += p0[r] + p1[r]; }
;             lrun = sum;
; #pragma unroll
;             for (int j = 0; j < 8; ++j) { pk[j >> 2][j & 3] = cvtpk_s(p0[2 * j], p0[2 * j + 1]); pk[2 + (j >> 2)][j & 3] = cvtpk_s(p1[2 * j], p1[2 * j + 1]); }
;             ATT_KRD(KBUF, 0, 1);
; #pragma unroll
;             for (int b2 = 0; b2 < 4; ++b2) vfa[b2] = *(const LAS bf16x8*)(lds + vr + b2 * 32 * VP);
;         }
;         __syncthreads();
;         int vs0 = 0, vs1 = VBUF, vs2 = 2 * VBUF;
;         int kq0 = 0, kq1 = KBUF, kq2 = 2 * KBUF;
; #pragma unroll 1
;         for (int t = 0; t < NT - 1; ++t) {
;             if (t + 3 < NT) *(LAS u32x4*)(lds + kq0 + kw) = kreg;
;             if (t + 2 < NT) { *(LAS u32x4*)(lds + vs2 + vw0) = vreg0; *(LAS u32x4*)(lds + vs2 + vw1) = vreg1; }
;             if (t + 4 < NT) kreg = *(const GAS u32x4*)(kg + (size_t)(t + 4) * 64 * 512);
;             if (t + 3 < NT) { vreg0 = *(const GAS u32x4*)(vg0 + (t + 3) * 64); vreg1 = *(const GAS u32x4*)(vg1 + (t + 3) * 64); }
	s_waitcnt vmcnt(1)
	v_mfma_f32_32x32x16_bf16 v[2:17], v[34:37], v[148:151], v[2:17]
	v_mfma_f32_32x32x16_bf16 v[18:33], v[38:41], v[148:151], v[18:33]
	s_nop 10
	v_max_f32_e32 v1, v3, v3
	v_max_f32_e32 v34, v2, v2
	v_max_f32_e32 v1, v34, v1
	v_max3_f32 v35, v4, v5, v19
	v_max3_f32 v1, v1, v18, v20
	v_max3_f32 v34, v35, v8, v9
	v_max3_f32 v1, v1, v21, v6
	v_max3_f32 v34, v34, v24, v25
	v_max3_f32 v1, v1, v7, v22
	v_max3_f32 v34, v34, v12, v13
	v_max3_f32 v1, v1, v23, v10
	v_max3_f32 v34, v34, v28, v29
	v_max3_f32 v1, v1, v11, v26
	v_max3_f32 v34, v34, v16, v17
	v_max3_f32 v1, v1, v27, v14
	v_max3_f32 v34, v34, v32, v33
	v_max3_f32 v1, v1, v15, v30
	v_max3_f32 v1, v1, v31, v34
	v_mov_b32_e32 v34, v1
	s_nop 1
	v_permlane32_swap_b32_e32 v1, v34
	v_max_f32_e32 v34, v34, v34
	v_max_f32_e32 v1, v1, v1
	v_max_f32_e32 v250, v1, v34
	v_sub_f32_e32 v1, v26, v250
	v_sub_f32_e32 v26, v27, v250
	v_sub_f32_e32 v27, v28, v250
	v_sub_f32_e32 v28, v29, v250
	v_sub_f32_e32 v29, v30, v250
	v_sub_f32_e32 v30, v31, v250
	v_sub_f32_e32 v31, v32, v250
	v_sub_f32_e32 v41, v18, v250
	v_sub_f32_e32 v42, v19, v250
	v_sub_f32_e32 v47, v2, v250
	v_sub_f32_e32 v32, v33, v250
	v_sub_f32_e32 v36, v13, v250
	v_sub_f32_e32 v48, v3, v250
	v_sub_f32_e32 v49, v4, v250
	v_exp_f32_e32 v3, v1
	v_exp_f32_e32 v4, v28
	v_exp_f32_e32 v13, v31
	v_exp_f32_e32 v1, v41
	v_exp_f32_e32 v28, v42
	v_exp_f32_e32 v31, v47
	v_sub_f32_e32 v33, v10, v250
	v_sub_f32_e32 v35, v12, v250
	v_sub_f32_e32 v43, v20, v250
	v_exp_f32_e32 v12, v32
	v_exp_f32_e32 v32, v48
	v_sub_f32_e32 v34, v11, v250
	v_sub_f32_e32 v38, v15, v250
	v_sub_f32_e32 v44, v21, v250
	v_sub_f32_e32 v50, v5, v250
	v_exp_f32_e32 v11, v29
	v_exp_f32_e32 v15, v33
	v_exp_f32_e32 v29, v43
	v_exp_f32_e32 v33, v49
	v_sub_f32_e32 v37, v14, v250
	v_sub_f32_e32 v22, v22, v250
	v_sub_f32_e32 v45, v23, v250
	v_exp_f32_e32 v10, v30
	v_exp_f32_e32 v14, v34
	v_exp_f32_e32 v30, v44
	v_exp_f32_e32 v34, v50
	v_sub_f32_e32 v6, v6, v250
	v_exp_f32_e32 v5, v27
	v_exp_f32_e32 v23, v22
	v_exp_f32_e32 v22, v45
	v_cvt_pk_bf16_f32 v172, v1, v28
	v_exp_f32_e32 v27, v6
	v_sub_f32_e32 v6, v7, v250
	v_add_f32_e32 v1, v1, v31
	v_exp_f32_e32 v2, v26
	v_exp_f32_e32 v26, v6
	v_sub_f32_e32 v6, v8, v250
	v_add_f32_e32 v1, 0, v1
	v_add_f32_e32 v8, v28, v32
	v_add_f32_e32 v1, v8, v1
	v_add_f32_e32 v8, v29, v33
	v_sub_f32_e32 v24, v24, v250
	v_sub_f32_e32 v46, v25, v250
	v_add_f32_e32 v1, v8, v1
	v_add_f32_e32 v8, v30, v34
	v_exp_f32_e32 v25, v24
	v_exp_f32_e32 v24, v46
	v_exp_f32_e32 v7, v6
	v_sub_f32_e32 v6, v9, v250
	v_add_f32_e32 v1, v8, v1
	v_pk_mov_b32 v[8:9], v[22:23], v[22:23] op_sel:[1,0]
	v_exp_f32_e32 v6, v6
	v_cvt_pk_bf16_f32 v174, v8, v9
	v_pk_mov_b32 v[8:9], v[26:27], v[26:27] op_sel:[1,0]
	v_sub_f32_e32 v39, v16, v250
	v_cvt_pk_bf16_f32 v202, v8, v9
	v_pk_add_f32 v[8:9], v[22:23], v[26:27]
	v_sub_f32_e32 v40, v17, v250
	v_add_f32_e32 v1, v9, v1
	v_add_f32_e32 v1, v8, v1
	v_pk_mov_b32 v[8:9], v[24:25], v[24:25] op_sel:[1,0]
	v_exp_f32_e32 v17, v35
	v_cvt_pk_bf16_f32 v175, v8, v9
	v_pk_mov_b32 v[8:9], v[6:7], v[6:7] op_sel:[1,0]
	v_pk_add_f32 v[6:7], v[24:25], v[6:7]
	v_exp_f32_e32 v16, v36
	v_add_f32_e32 v1, v7, v1
	v_add_f32_e32 v1, v6, v1
	v_pk_mov_b32 v[6:7], v[2:3], v[2:3] op_sel:[1,0]
	v_pk_add_f32 v[2:3], v[2:3], v[14:15]
	v_exp_f32_e32 v19, v37
	v_add_f32_e32 v1, v3, v1
	v_add_f32_e32 v1, v2, v1
	v_pk_mov_b32 v[2:3], v[4:5], v[4:5] op_sel:[1,0]
	v_exp_f32_e32 v18, v38
	v_cvt_pk_bf16_f32 v165, v2, v3
	v_pk_mov_b32 v[2:3], v[16:17], v[16:17] op_sel:[1,0]
	v_exp_f32_e32 v21, v39
	v_cvt_pk_bf16_f32 v181, v2, v3
	v_pk_add_f32 v[2:3], v[4:5], v[16:17]
	v_exp_f32_e32 v20, v40
	v_add_f32_e32 v1, v3, v1
	v_add_f32_e32 v1, v2, v1
	v_pk_mov_b32 v[2:3], v[10:11], v[10:11] op_sel:[1,0]
	v_xor_b32_e32 v64, 0x80000000, v250
	v_cvt_pk_bf16_f32 v166, v2, v3
	v_pk_mov_b32 v[2:3], v[18:19], v[18:19] op_sel:[1,0]
	v_cvt_pk_bf16_f32 v164, v6, v7
	v_cvt_pk_bf16_f32 v182, v2, v3
	v_pk_add_f32 v[2:3], v[10:11], v[18:19]
	v_pk_mov_b32 v[6:7], v[14:15], v[14:15] op_sel:[1,0]
	v_add_f32_e32 v1, v3, v1
	v_add_f32_e32 v1, v2, v1
	v_pk_mov_b32 v[2:3], v[12:13], v[12:13] op_sel:[1,0]
	v_cvt_pk_bf16_f32 v173, v29, v30
	v_cvt_pk_bf16_f32 v167, v2, v3
	v_pk_mov_b32 v[2:3], v[20:21], v[20:21] op_sel:[1,0]
	v_cvt_pk_bf16_f32 v200, v31, v32
	v_cvt_pk_bf16_f32 v183, v2, v3
	v_pk_add_f32 v[2:3], v[12:13], v[20:21]
	v_cvt_pk_bf16_f32 v201, v33, v34
	v_add_f32_e32 v1, v3, v1
	v_cvt_pk_bf16_f32 v203, v8, v9
	v_cvt_pk_bf16_f32 v180, v6, v7
	v_add_f32_e32 v249, v2, v1
	v_mov_b32_e32 v1, v0
	v_mov_b32_e32 v2, v0
	v_mov_b32_e32 v3, v0
	v_mov_b32_e32 v4, v0
	v_mov_b32_e32 v5, v0
	v_mov_b32_e32 v6, v0
	v_mov_b32_e32 v7, v0
	v_mov_b32_e32 v8, v0
	v_mov_b32_e32 v9, v0
	v_mov_b32_e32 v10, v0
	v_mov_b32_e32 v11, v0
	v_mov_b32_e32 v12, v0
	v_mov_b32_e32 v13, v0
	v_mov_b32_e32 v14, v0
	v_mov_b32_e32 v15, v0
	v_mov_b32_e32 v48, v0
	v_mov_b32_e32 v49, v0
	v_mov_b32_e32 v50, v0
	v_mov_b32_e32 v32, v0
	v_mov_b32_e32 v33, v0
	v_mov_b32_e32 v34, v0
	v_mov_b32_e32 v35, v0
	v_mov_b32_e32 v36, v0
	v_mov_b32_e32 v37, v0
	v_mov_b32_e32 v38, v0
	v_mov_b32_e32 v39, v0
	v_mov_b32_e32 v40, v0
	v_mov_b32_e32 v41, v0
	v_mov_b32_e32 v42, v0
	v_mov_b32_e32 v43, v0
	v_mov_b32_e32 v44, v0
	v_mov_b32_e32 v45, v0
	v_mov_b32_e32 v46, v0
	v_mov_b32_e32 v47, v0
	v_mov_b32_e32 v16, v0
	v_mov_b32_e32 v17, v0
	v_mov_b32_e32 v18, v0
	v_mov_b32_e32 v19, v0
	v_mov_b32_e32 v20, v0
	v_mov_b32_e32 v21, v0
	v_mov_b32_e32 v22, v0
	v_mov_b32_e32 v23, v0
	v_mov_b32_e32 v24, v0
	v_mov_b32_e32 v25, v0
	v_mov_b32_e32 v26, v0
	v_mov_b32_e32 v27, v0
	v_mov_b32_e32 v28, v0
	v_mov_b32_e32 v29, v0
	v_mov_b32_e32 v30, v0
	v_mov_b32_e32 v31, v0
	v_mov_b32_e32 v65, v64
	v_mov_b32_e32 v66, v64
	v_mov_b32_e32 v67, v64
	v_mov_b32_e32 v68, v64
	v_mov_b32_e32 v69, v64
	v_mov_b32_e32 v70, v64
	v_mov_b32_e32 v71, v64
	v_mov_b32_e32 v72, v64
	v_mov_b32_e32 v73, v64
	v_mov_b32_e32 v74, v64
	v_mov_b32_e32 v75, v64
	v_mov_b32_e32 v76, v64
	v_mov_b32_e32 v77, v64
	v_mov_b32_e32 v78, v64
	v_mov_b32_e32 v79, v64
.LBB0_335:
	s_mov_b32 s61, s50
	s_mov_b32 s50, s29
	s_mov_b32 s65, s28
	v_mfma_f32_32x32x16_bf16 v[96:111], v[156:159], v[136:139], v[64:79]
	v_mfma_f32_32x32x16_bf16 v[80:95], v[160:163], v[136:139], v[64:79]
	s_add_i32 s29, s57, 3
	s_cmp_lt_u32 s29, s38
	s_cselect_b64 s[30:31], -1, 0
	s_cmp_ge_u32 s29, s38
	s_cbranch_scc1 .Lmy_skip_kw
	v_add_u32_e32 v156, s60, v248
	s_waitcnt vmcnt(0)
	ds_write_b128 v156, v[152:155]

; __global__ void __launch_bounds__(512, 2) fwd_megakernel(mk::Params p) {
;     ...
;                 for (int u = vcu; u < NB * 4 * nqb; u += G) {
;                     const int qb = u % nqb, bh = u / nqb;
;                     attn_unit(lds, (bf16_t*)(gb + GB_MIX), (const bf16_t*)(gb + GB_K), (const bf16_t*)(gb + GB_VT), bh >> 2, bh & 3, qb, lgS, lam, oscale, p.subln_g + l * 128,
;                               (float*)(p.out + (size_t)48 * MiB) + (size_t)vcu * 64 * 512);
;                 }
;                 __syncthreads();
.LBB0_351:
	s_setprio 0
	s_mov_b64 s[6:7], -1
	v_mov_b64_e32 v[230:231], 0x200
	v_mov_b64_e32 v[232:233], 0x1ff
	s_barrier
